# main epilogue prefetches the B tile two rounds ahead into the memory-side cache (2 dword loads per CU slice)
# baseline (speedup 1.0000x reference)
.LBB0_372:
	s_add_u32 s8, s6, 0xfff80080
	s_addc_u32 s9, s7, -1
	s_add_i32 s21, 0, 0x10000
	v_add_u32_e32 v143, s21, v167
	ds_read_b128 v[148:151], v143
	ds_read_b128 v[152:155], v143 offset:1024
	ds_read_b128 v[156:159], v143 offset:2048
	ds_read_b128 v[160:163], v143 offset:3072
	s_cmp_eq_u32 s20, 28
	s_cselect_b32 s11, s17, s9
	s_cselect_b32 s10, s16, s8
	s_cselect_b32 s9, s19, s15
	s_cselect_b32 s8, s18, s13
	v_lshl_add_u64 v[164:165], s[6:7], 0, v[138:139]
	s_add_i32 m0, s40, 0xc000
	ds_read_b128 v[172:175], v171
	ds_read_b128 v[180:183], v171 offset:1024
	ds_read_b128 v[184:187], v171 offset:2048
	ds_read_b128 v[188:191], v171 offset:3072
	ds_read_b128 v[192:195], v171 offset:4096
	ds_read_b128 v[196:199], v171 offset:5120
	ds_read_b128 v[200:203], v171 offset:6144
	ds_read_b128 v[204:207], v171 offset:7168
	global_load_lds_dwordx4 v[164:165], off
	v_lshl_add_u64 v[164:165], s[6:7], 0, v[140:141]
	s_add_i32 m0, s40, 0xe000
	s_nop 0
	global_load_lds_dwordx4 v[164:165], off
	s_waitcnt lgkmcnt(8)
	s_barrier
	s_waitcnt lgkmcnt(0)
	s_setprio 1
	s_waitcnt lgkmcnt(0)
	v_mfma_f32_16x16x32_bf16 v[126:129], v[148:151], v[172:175], v[126:129]
	v_mfma_f32_16x16x32_bf16 v[122:125], v[156:159], v[172:175], v[122:125]
	v_mfma_f32_16x16x32_bf16 v[110:113], v[148:151], v[184:187], v[110:113]
	v_mfma_f32_16x16x32_bf16 v[106:109], v[156:159], v[184:187], v[106:109]
	v_mfma_f32_16x16x32_bf16 v[94:97], v[148:151], v[192:195], v[94:97]
	v_mfma_f32_16x16x32_bf16 v[90:93], v[156:159], v[192:195], v[90:93]
	v_mfma_f32_16x16x32_bf16 v[78:81], v[148:151], v[200:203], v[78:81]
	v_mfma_f32_16x16x32_bf16 v[74:77], v[156:159], v[200:203], v[74:77]
	v_mfma_f32_16x16x32_bf16 v[126:129], v[152:155], v[180:183], v[126:129]
	v_mfma_f32_16x16x32_bf16 v[122:125], v[160:163], v[180:183], v[122:125]
	v_mfma_f32_16x16x32_bf16 v[110:113], v[152:155], v[188:191], v[110:113]
	v_mfma_f32_16x16x32_bf16 v[106:109], v[160:163], v[188:191], v[106:109]
	v_mfma_f32_16x16x32_bf16 v[94:97], v[152:155], v[196:199], v[94:97]
	v_mfma_f32_16x16x32_bf16 v[90:93], v[160:163], v[196:199], v[90:93]
	v_mfma_f32_16x16x32_bf16 v[78:81], v[152:155], v[204:207], v[78:81]
	v_mfma_f32_16x16x32_bf16 v[74:77], v[160:163], v[204:207], v[74:77]
	s_setprio 0
	s_barrier
	s_add_i32 s24, 0, 0x14000
	s_add_i32 s21, s21, s39
	v_add_u32_e32 v143, s24, v167
	v_lshl_add_u64 v[164:165], s[8:9], 0, v[134:135]
	s_mov_b32 m0, s21
	ds_read_b128 v[208:211], v143
	ds_read_b128 v[212:215], v143 offset:1024
	ds_read_b128 v[216:219], v143 offset:2048
	ds_read_b128 v[220:223], v143 offset:3072
	global_load_lds_dwordx4 v[164:165], off
	v_lshl_add_u64 v[176:177], s[8:9], 0, v[130:131]
	s_add_i32 m0, s21, 0x2000
	s_nop 0
	global_load_lds_dwordx4 v[176:177], off
	s_barrier
	s_waitcnt lgkmcnt(0)
	s_setprio 1
	s_waitcnt lgkmcnt(0)
	v_mfma_f32_16x16x32_bf16 v[118:121], v[208:211], v[172:175], v[118:121]
	v_mfma_f32_16x16x32_bf16 v[114:117], v[216:219], v[172:175], v[114:117]
	v_mfma_f32_16x16x32_bf16 v[102:105], v[208:211], v[184:187], v[102:105]
	v_mfma_f32_16x16x32_bf16 v[98:101], v[216:219], v[184:187], v[98:101]
	v_mfma_f32_16x16x32_bf16 v[86:89], v[208:211], v[192:195], v[86:89]
	v_mfma_f32_16x16x32_bf16 v[82:85], v[216:219], v[192:195], v[82:85]
	v_mfma_f32_16x16x32_bf16 v[70:73], v[208:211], v[200:203], v[70:73]
	v_mfma_f32_16x16x32_bf16 v[66:69], v[216:219], v[200:203], v[66:69]
	v_mfma_f32_16x16x32_bf16 v[118:121], v[212:215], v[180:183], v[118:121]
	v_mfma_f32_16x16x32_bf16 v[114:117], v[220:223], v[180:183], v[114:117]
	v_mfma_f32_16x16x32_bf16 v[102:105], v[212:215], v[188:191], v[102:105]
	v_mfma_f32_16x16x32_bf16 v[98:101], v[220:223], v[188:191], v[98:101]
	v_mfma_f32_16x16x32_bf16 v[86:89], v[212:215], v[196:199], v[86:89]
	v_mfma_f32_16x16x32_bf16 v[82:85], v[220:223], v[196:199], v[82:85]
	v_mfma_f32_16x16x32_bf16 v[70:73], v[212:215], v[204:207], v[70:73]
	v_mfma_f32_16x16x32_bf16 v[66:69], v[220:223], v[204:207], v[66:69]
	s_setprio 0
	s_mov_b32 m0, s40
	v_lshl_add_u64 v[224:225], s[10:11], 0, v[136:137]
	s_barrier
	ds_read_b128 v[172:175], v171 offset:16384
	ds_read_b128 v[180:183], v171 offset:17408
	ds_read_b128 v[184:187], v171 offset:18432
	ds_read_b128 v[188:191], v171 offset:19456
	ds_read_b128 v[192:195], v171 offset:20480
	ds_read_b128 v[196:199], v171 offset:21504
	ds_read_b128 v[200:203], v171 offset:22528
	ds_read_b128 v[204:207], v171 offset:23552
	global_load_lds_dwordx4 v[224:225], off
	v_lshl_add_u64 v[236:237], s[10:11], 0, v[132:133]
	s_mov_b32 m0, s41
	s_nop 0
	global_load_lds_dwordx4 v[236:237], off
	s_barrier
	s_waitcnt lgkmcnt(0)
	s_setprio 1
	s_waitcnt lgkmcnt(0)
	v_mfma_f32_16x16x32_bf16 v[62:65], v[148:151], v[172:175], v[62:65]
	v_mfma_f32_16x16x32_bf16 v[58:61], v[156:159], v[172:175], v[58:61]
	v_mfma_f32_16x16x32_bf16 v[46:49], v[148:151], v[184:187], v[46:49]
	v_mfma_f32_16x16x32_bf16 v[42:45], v[156:159], v[184:187], v[42:45]
	v_mfma_f32_16x16x32_bf16 v[28:31], v[148:151], v[192:195], v[28:31]
	v_mfma_f32_16x16x32_bf16 v[24:27], v[156:159], v[192:195], v[24:27]
	v_mfma_f32_16x16x32_bf16 v[12:15], v[148:151], v[200:203], v[12:15]
	v_mfma_f32_16x16x32_bf16 v[8:11], v[156:159], v[200:203], v[8:11]
	v_mfma_f32_16x16x32_bf16 v[62:65], v[152:155], v[180:183], v[62:65]
	v_mfma_f32_16x16x32_bf16 v[58:61], v[160:163], v[180:183], v[58:61]
	v_mfma_f32_16x16x32_bf16 v[46:49], v[152:155], v[188:191], v[46:49]
	v_mfma_f32_16x16x32_bf16 v[42:45], v[160:163], v[188:191], v[42:45]
	v_mfma_f32_16x16x32_bf16 v[28:31], v[152:155], v[196:199], v[28:31]
	v_mfma_f32_16x16x32_bf16 v[24:27], v[160:163], v[196:199], v[24:27]
	v_mfma_f32_16x16x32_bf16 v[12:15], v[152:155], v[204:207], v[12:15]
	v_mfma_f32_16x16x32_bf16 v[8:11], v[160:163], v[204:207], v[8:11]
	s_setprio 0
	s_barrier
	s_add_u32 s22, s8, 0x80000
	s_addc_u32 s23, s9, 0
	s_add_i32 s21, s24, s39
	v_lshl_add_u64 v[148:149], s[22:23], 0, v[134:135]
	s_mov_b32 m0, s21
	s_nop 0
	global_load_lds_dwordx4 v[148:149], off
	v_lshl_add_u64 v[148:149], s[22:23], 0, v[130:131]
	s_add_i32 m0, s21, 0x2000
	s_nop 0
	global_load_lds_dwordx4 v[148:149], off
	s_waitcnt vmcnt(6)
	s_barrier
	s_setprio 1
	v_mfma_f32_16x16x32_bf16 v[54:57], v[208:211], v[172:175], v[54:57]
	v_mfma_f32_16x16x32_bf16 v[50:53], v[216:219], v[172:175], v[50:53]
	v_mfma_f32_16x16x32_bf16 v[38:41], v[208:211], v[184:187], v[38:41]
	v_mfma_f32_16x16x32_bf16 v[34:37], v[216:219], v[184:187], v[34:37]
	v_mfma_f32_16x16x32_bf16 v[20:23], v[208:211], v[192:195], v[20:23]
	v_mfma_f32_16x16x32_bf16 v[16:19], v[216:219], v[192:195], v[16:19]
	v_mfma_f32_16x16x32_bf16 v[4:7], v[208:211], v[200:203], v[4:7]
	v_mfma_f32_16x16x32_bf16 v[0:3], v[216:219], v[200:203], v[0:3]
	v_mfma_f32_16x16x32_bf16 v[54:57], v[212:215], v[180:183], v[54:57]
	v_mfma_f32_16x16x32_bf16 v[50:53], v[220:223], v[180:183], v[50:53]
	v_mfma_f32_16x16x32_bf16 v[38:41], v[212:215], v[188:191], v[38:41]
	v_mfma_f32_16x16x32_bf16 v[34:37], v[220:223], v[188:191], v[34:37]
	v_mfma_f32_16x16x32_bf16 v[20:23], v[212:215], v[196:199], v[20:23]
	v_mfma_f32_16x16x32_bf16 v[16:19], v[220:223], v[196:199], v[16:19]
	v_mfma_f32_16x16x32_bf16 v[4:7], v[212:215], v[204:207], v[4:7]
	v_mfma_f32_16x16x32_bf16 v[0:3], v[220:223], v[204:207], v[0:3]
	s_setprio 0
	s_add_i32 s21, 0, 0x18000
	v_add_u32_e32 v143, s21, v167
	s_barrier
	ds_read_b128 v[148:151], v143
	ds_read_b128 v[152:155], v143 offset:1024
	ds_read_b128 v[156:159], v143 offset:2048
	ds_read_b128 v[160:163], v143 offset:3072
	s_add_u32 s10, s10, 0x80000
	s_addc_u32 s11, s11, 0
	s_mov_b32 m0, s42
	v_lshl_add_u64 v[208:209], s[10:11], 0, v[136:137]
	ds_read_b128 v[172:175], v171 offset:32768
	ds_read_b128 v[180:183], v171 offset:33792
	ds_read_b128 v[184:187], v171 offset:34816
	ds_read_b128 v[188:191], v171 offset:35840
	ds_read_b128 v[192:195], v171 offset:36864
	ds_read_b128 v[196:199], v171 offset:37888
	ds_read_b128 v[200:203], v171 offset:38912
	ds_read_b128 v[204:207], v171 offset:39936
	global_load_lds_dwordx4 v[208:209], off
	v_lshl_add_u64 v[208:209], s[10:11], 0, v[132:133]
	s_mov_b32 m0, s43
	s_nop 0
	global_load_lds_dwordx4 v[208:209], off
	s_waitcnt lgkmcnt(8)
	s_barrier
	s_waitcnt lgkmcnt(0)
	s_setprio 1
	s_waitcnt lgkmcnt(0)
	v_mfma_f32_16x16x32_bf16 v[126:129], v[148:151], v[172:175], v[126:129]
	v_mfma_f32_16x16x32_bf16 v[122:125], v[156:159], v[172:175], v[122:125]
	v_mfma_f32_16x16x32_bf16 v[110:113], v[148:151], v[184:187], v[110:113]
	v_mfma_f32_16x16x32_bf16 v[106:109], v[156:159], v[184:187], v[106:109]
	v_mfma_f32_16x16x32_bf16 v[94:97], v[148:151], v[192:195], v[94:97]
	v_mfma_f32_16x16x32_bf16 v[90:93], v[156:159], v[192:195], v[90:93]
	v_mfma_f32_16x16x32_bf16 v[78:81], v[148:151], v[200:203], v[78:81]
	v_mfma_f32_16x16x32_bf16 v[74:77], v[156:159], v[200:203], v[74:77]
	v_mfma_f32_16x16x32_bf16 v[126:129], v[152:155], v[180:183], v[126:129]
	v_mfma_f32_16x16x32_bf16 v[122:125], v[160:163], v[180:183], v[122:125]
	v_mfma_f32_16x16x32_bf16 v[110:113], v[152:155], v[188:191], v[110:113]
	v_mfma_f32_16x16x32_bf16 v[106:109], v[160:163], v[188:191], v[106:109]
	v_mfma_f32_16x16x32_bf16 v[94:97], v[152:155], v[196:199], v[94:97]
	v_mfma_f32_16x16x32_bf16 v[90:93], v[160:163], v[196:199], v[90:93]
	v_mfma_f32_16x16x32_bf16 v[78:81], v[152:155], v[204:207], v[78:81]
	v_mfma_f32_16x16x32_bf16 v[74:77], v[160:163], v[204:207], v[74:77]
	s_setprio 0
	s_barrier
	s_add_i32 s10, 0, 0x1c000
	s_add_i32 s11, s21, s39
	v_add_u32_e32 v143, s10, v167
	v_lshl_add_u64 v[164:165], v[164:165], 0, s[88:89]
	s_mov_b32 m0, s11
	ds_read_b128 v[208:211], v143
	ds_read_b128 v[212:215], v143 offset:1024
	ds_read_b128 v[216:219], v143 offset:2048
	ds_read_b128 v[220:223], v143 offset:3072
	global_load_lds_dwordx4 v[164:165], off
	v_lshl_add_u64 v[164:165], v[176:177], 0, s[88:89]
	s_add_i32 m0, s11, 0x2000
	s_nop 0
	global_load_lds_dwordx4 v[164:165], off
	s_barrier
	s_waitcnt lgkmcnt(0)
	s_setprio 1
	s_waitcnt lgkmcnt(0)
	v_mfma_f32_16x16x32_bf16 v[118:121], v[208:211], v[172:175], v[118:121]
	v_mfma_f32_16x16x32_bf16 v[114:117], v[216:219], v[172:175], v[114:117]
	v_mfma_f32_16x16x32_bf16 v[102:105], v[208:211], v[184:187], v[102:105]
	v_mfma_f32_16x16x32_bf16 v[98:101], v[216:219], v[184:187], v[98:101]
	v_mfma_f32_16x16x32_bf16 v[86:89], v[208:211], v[192:195], v[86:89]
	v_mfma_f32_16x16x32_bf16 v[82:85], v[216:219], v[192:195], v[82:85]
	v_mfma_f32_16x16x32_bf16 v[70:73], v[208:211], v[200:203], v[70:73]
	v_mfma_f32_16x16x32_bf16 v[66:69], v[216:219], v[200:203], v[66:69]
	v_mfma_f32_16x16x32_bf16 v[118:121], v[212:215], v[180:183], v[118:121]
	v_mfma_f32_16x16x32_bf16 v[114:117], v[220:223], v[180:183], v[114:117]
	v_mfma_f32_16x16x32_bf16 v[102:105], v[212:215], v[188:191], v[102:105]
	v_mfma_f32_16x16x32_bf16 v[98:101], v[220:223], v[188:191], v[98:101]
	v_mfma_f32_16x16x32_bf16 v[86:89], v[212:215], v[196:199], v[86:89]
	v_mfma_f32_16x16x32_bf16 v[82:85], v[220:223], v[196:199], v[82:85]
	v_mfma_f32_16x16x32_bf16 v[70:73], v[212:215], v[204:207], v[70:73]
	v_mfma_f32_16x16x32_bf16 v[66:69], v[220:223], v[204:207], v[66:69]
	s_setprio 0
	s_mov_b32 m0, s46
	v_lshl_add_u64 v[164:165], v[224:225], 0, s[88:89]
	s_barrier
	ds_read_b128 v[172:175], v171 offset:49152
	ds_read_b128 v[180:183], v171 offset:50176
	ds_read_b128 v[184:187], v171 offset:51200
	ds_read_b128 v[188:191], v171 offset:52224
	ds_read_b128 v[192:195], v171 offset:53248
	ds_read_b128 v[196:199], v171 offset:54272
	ds_read_b128 v[200:203], v171 offset:55296
	ds_read_b128 v[204:207], v171 offset:56320
	global_load_lds_dwordx4 v[164:165], off
	v_lshl_add_u64 v[164:165], v[236:237], 0, s[88:89]
	s_mov_b32 m0, s47
	s_nop 0
	global_load_lds_dwordx4 v[164:165], off
	s_barrier
	s_waitcnt lgkmcnt(0)
	s_setprio 1
	s_waitcnt lgkmcnt(0)
	v_mfma_f32_16x16x32_bf16 v[62:65], v[148:151], v[172:175], v[62:65]
	v_mfma_f32_16x16x32_bf16 v[58:61], v[156:159], v[172:175], v[58:61]
	v_mfma_f32_16x16x32_bf16 v[46:49], v[148:151], v[184:187], v[46:49]
	v_mfma_f32_16x16x32_bf16 v[42:45], v[156:159], v[184:187], v[42:45]
	v_mfma_f32_16x16x32_bf16 v[28:31], v[148:151], v[192:195], v[28:31]
	v_mfma_f32_16x16x32_bf16 v[24:27], v[156:159], v[192:195], v[24:27]
	v_mfma_f32_16x16x32_bf16 v[12:15], v[148:151], v[200:203], v[12:15]
	v_mfma_f32_16x16x32_bf16 v[8:11], v[156:159], v[200:203], v[8:11]
	v_mfma_f32_16x16x32_bf16 v[62:65], v[152:155], v[180:183], v[62:65]
	v_mfma_f32_16x16x32_bf16 v[58:61], v[160:163], v[180:183], v[58:61]
	v_mfma_f32_16x16x32_bf16 v[46:49], v[152:155], v[188:191], v[46:49]
	v_mfma_f32_16x16x32_bf16 v[42:45], v[160:163], v[188:191], v[42:45]
	v_mfma_f32_16x16x32_bf16 v[28:31], v[152:155], v[196:199], v[28:31]
	v_mfma_f32_16x16x32_bf16 v[24:27], v[160:163], v[196:199], v[24:27]
	v_mfma_f32_16x16x32_bf16 v[12:15], v[152:155], v[204:207], v[12:15]
	v_mfma_f32_16x16x32_bf16 v[8:11], v[160:163], v[204:207], v[8:11]
	s_setprio 0
	s_barrier
	s_add_u32 s8, s8, 0x80080
	s_addc_u32 s9, s9, 0
	s_add_i32 s10, s10, s39
	v_lshl_add_u64 v[148:149], s[8:9], 0, v[134:135]
	s_mov_b32 m0, s10
	s_nop 0
	global_load_lds_dwordx4 v[148:149], off
	v_lshl_add_u64 v[148:149], s[8:9], 0, v[130:131]
	s_add_i32 m0, s10, 0x2000
	s_nop 0
	global_load_lds_dwordx4 v[148:149], off
	s_waitcnt vmcnt(6)
	s_barrier
	s_setprio 1
	v_mfma_f32_16x16x32_bf16 v[54:57], v[208:211], v[172:175], v[54:57]
	v_mfma_f32_16x16x32_bf16 v[50:53], v[216:219], v[172:175], v[50:53]
	v_mfma_f32_16x16x32_bf16 v[38:41], v[208:211], v[184:187], v[38:41]
	v_mfma_f32_16x16x32_bf16 v[34:37], v[216:219], v[184:187], v[34:37]
	v_mfma_f32_16x16x32_bf16 v[20:23], v[208:211], v[192:195], v[20:23]
	v_mfma_f32_16x16x32_bf16 v[16:19], v[216:219], v[192:195], v[16:19]
	v_mfma_f32_16x16x32_bf16 v[4:7], v[208:211], v[200:203], v[4:7]
	v_mfma_f32_16x16x32_bf16 v[0:3], v[216:219], v[200:203], v[0:3]
	v_mfma_f32_16x16x32_bf16 v[54:57], v[212:215], v[180:183], v[54:57]
	v_mfma_f32_16x16x32_bf16 v[50:53], v[220:223], v[180:183], v[50:53]
	v_mfma_f32_16x16x32_bf16 v[38:41], v[212:215], v[188:191], v[38:41]
	v_mfma_f32_16x16x32_bf16 v[34:37], v[220:223], v[188:191], v[34:37]
	v_mfma_f32_16x16x32_bf16 v[20:23], v[212:215], v[196:199], v[20:23]
	v_mfma_f32_16x16x32_bf16 v[16:19], v[220:223], v[196:199], v[16:19]
	v_mfma_f32_16x16x32_bf16 v[4:7], v[212:215], v[204:207], v[4:7]
	v_mfma_f32_16x16x32_bf16 v[0:3], v[220:223], v[204:207], v[0:3]
	s_setprio 0
	s_add_i32 s20, s20, 2
	s_add_u32 s6, s6, 0x100
	s_addc_u32 s7, s7, 0
	s_add_u32 s13, s13, 0x100
	s_addc_u32 s15, s15, 0
	s_cmp_gt_u32 s20, 29
	s_barrier
	s_cbranch_scc0 .LBB0_372
	s_sub_i32 s6, s51, 8
	s_cmp_lt_u32 s6, 8
	s_cbranch_scc1 .Lmain_old
	s_sub_i32 s6, s51, 32
	s_cmp_lt_u32 s6, 12
	s_cbranch_scc1 .Lmain_kv
	v_mbcnt_lo_u32_b32 v217, -1, 0
	v_mbcnt_hi_u32_b32 v217, -1, v217
	s_add_i32 s24, s51, 8
	s_cmp_lt_u32 s24, 92
	s_cbranch_scc0 .Lmain_nopf
	s_lshl_b32 s24, s24, 20
	s_and_b32 s25, s33, 63
	s_lshl_b32 s25, s25, 14
	s_add_i32 s24, s24, s25
	s_add_u32 s24, s48, s24
	s_addc_u32 s25, s49, 0
	v_lshlrev_b32_e32 v218, 7, v217
	global_load_dword v219, v218, s[24:25]
	s_add_u32 s24, s24, 0x2000
	s_addc_u32 s25, s25, 0
	global_load_dword v219, v218, s[24:25]
.Lmain_nopf:
	v_lshrrev_b32_e32 v208, 4, v217
	v_bfe_u32 v209, v217, 2, 2
	v_and_b32_e32 v210, 3, v217
	v_lshl_add_u32 v216, v208, 2, v209
	v_lshl_add_u32 v217, v210, 4, v216
	v_lshlrev_b32_e32 v217, 2, v217
	v_add_u32_e32 v216, s45, v216
	v_lshlrev_b32_e32 v210, 4, v210
	s_lshl_b32 s6, s44, 6
	v_add_u32_e32 v210, s6, v210
	s_cmp_ge_u32 s51, 0x44
	s_cbranch_scc1 .Lmain_sig
	s_sub_i32 s6, s51, 44
	s_mov_b32 s7, 0x25e51000
	s_mov_b32 s13, 0x15e51000
	s_cmp_lt_i32 s6, 0
	s_cselect_b32 s6, s51, s6
	s_cselect_b32 s7, s13, s7
	s_lshr_b32 s13, s6, 3
	s_lshl_b32 s13, s13, 26
	s_add_i32 s7, s7, s13
	s_and_b32 s6, s6, 7
	s_lshl_b32 s6, s6, 9
	s_add_i32 s7, s7, s6
	s_lshl_b32 s6, s31, 20
	s_add_i32 s7, s7, s6
	s_add_u32 s22, s76, s7
	s_addc_u32 s23, s77, 0
	v_lshl_add_u32 v216, v216, 12, v210
	s_lshr_b32 s6, s51, 3
	s_cmp_eq_u32 s6, 3
	s_cbranch_scc1 .Lmain_q
	s_add_u32 s10, s22, 0
	s_addc_u32 s11, s23, 0
	v_cvt_pk_bf16_f32 v148, v126, v127
	v_cvt_pk_bf16_f32 v149, v128, v129
	v_cvt_pk_bf16_f32 v150, v122, v123
	v_cvt_pk_bf16_f32 v151, v124, v125
	ds_bpermute_b32 v180, v217, v148
	ds_bpermute_b32 v181, v217, v149
	ds_bpermute_b32 v182, v217, v150
	ds_bpermute_b32 v183, v217, v151
	v_cvt_pk_bf16_f32 v152, v118, v119
	v_cvt_pk_bf16_f32 v153, v120, v121
	v_cvt_pk_bf16_f32 v154, v114, v115
	v_cvt_pk_bf16_f32 v155, v116, v117
	ds_bpermute_b32 v184, v217, v152
	ds_bpermute_b32 v185, v217, v153
	ds_bpermute_b32 v186, v217, v154
	ds_bpermute_b32 v187, v217, v155
	s_add_u32 s20, s22, 0x10000
	s_addc_u32 s21, s23, 0
	v_cvt_pk_bf16_f32 v156, v110, v111
	v_cvt_pk_bf16_f32 v157, v112, v113
	v_cvt_pk_bf16_f32 v158, v106, v107
	v_cvt_pk_bf16_f32 v159, v108, v109
	ds_bpermute_b32 v188, v217, v156
	ds_bpermute_b32 v189, v217, v157
	ds_bpermute_b32 v190, v217, v158
	ds_bpermute_b32 v191, v217, v159
	v_cvt_pk_bf16_f32 v160, v102, v103
	v_cvt_pk_bf16_f32 v161, v104, v105
	v_cvt_pk_bf16_f32 v162, v98, v99
	v_cvt_pk_bf16_f32 v163, v100, v101
	ds_bpermute_b32 v192, v217, v160
	ds_bpermute_b32 v193, v217, v161
	ds_bpermute_b32 v194, v217, v162
	ds_bpermute_b32 v195, v217, v163
	s_waitcnt lgkmcnt(0)
	global_store_dwordx4 v216, v[180:183], s[10:11] sc0 sc1
	global_store_dwordx4 v216, v[184:187], s[10:11] offset:256 sc0 sc1
	global_store_dwordx4 v216, v[188:191], s[20:21] sc0 sc1
	global_store_dwordx4 v216, v[192:195], s[20:21] offset:256 sc0 sc1
	s_add_u32 s10, s22, 0x20000
	s_addc_u32 s11, s23, 0
	v_cvt_pk_bf16_f32 v148, v94, v95
	v_cvt_pk_bf16_f32 v149, v96, v97
	v_cvt_pk_bf16_f32 v150, v90, v91
	v_cvt_pk_bf16_f32 v151, v92, v93
	ds_bpermute_b32 v180, v217, v148
	ds_bpermute_b32 v181, v217, v149
	ds_bpermute_b32 v182, v217, v150
	ds_bpermute_b32 v183, v217, v151
	v_cvt_pk_bf16_f32 v152, v86, v87
	v_cvt_pk_bf16_f32 v153, v88, v89
	v_cvt_pk_bf16_f32 v154, v82, v83
	v_cvt_pk_bf16_f32 v155, v84, v85
	ds_bpermute_b32 v184, v217, v152
	ds_bpermute_b32 v185, v217, v153
	ds_bpermute_b32 v186, v217, v154
	ds_bpermute_b32 v187, v217, v155
	s_add_u32 s20, s22, 0x30000
	s_addc_u32 s21, s23, 0
	v_cvt_pk_bf16_f32 v156, v78, v79
	v_cvt_pk_bf16_f32 v157, v80, v81
	v_cvt_pk_bf16_f32 v158, v74, v75
	v_cvt_pk_bf16_f32 v159, v76, v77
	ds_bpermute_b32 v188, v217, v156
	ds_bpermute_b32 v189, v217, v157
	ds_bpermute_b32 v190, v217, v158
	ds_bpermute_b32 v191, v217, v159
	v_cvt_pk_bf16_f32 v160, v70, v71
	v_cvt_pk_bf16_f32 v161, v72, v73
	v_cvt_pk_bf16_f32 v162, v66, v67
	v_cvt_pk_bf16_f32 v163, v68, v69
	ds_bpermute_b32 v192, v217, v160
	ds_bpermute_b32 v193, v217, v161
	ds_bpermute_b32 v194, v217, v162
	ds_bpermute_b32 v195, v217, v163
	s_waitcnt lgkmcnt(0)
	global_store_dwordx4 v216, v[180:183], s[10:11] sc0 sc1
	global_store_dwordx4 v216, v[184:187], s[10:11] offset:256 sc0 sc1
	global_store_dwordx4 v216, v[188:191], s[20:21] sc0 sc1
	global_store_dwordx4 v216, v[192:195], s[20:21] offset:256 sc0 sc1
	s_add_u32 s10, s22, 0x80000
	s_addc_u32 s11, s23, 0
	v_cvt_pk_bf16_f32 v148, v62, v63
	v_cvt_pk_bf16_f32 v149, v64, v65
	v_cvt_pk_bf16_f32 v150, v58, v59
	v_cvt_pk_bf16_f32 v151, v60, v61
	ds_bpermute_b32 v180, v217, v148
	ds_bpermute_b32 v181, v217, v149
	ds_bpermute_b32 v182, v217, v150
	ds_bpermute_b32 v183, v217, v151
	v_cvt_pk_bf16_f32 v152, v54, v55
	v_cvt_pk_bf16_f32 v153, v56, v57
	v_cvt_pk_bf16_f32 v154, v50, v51
	v_cvt_pk_bf16_f32 v155, v52, v53
	ds_bpermute_b32 v184, v217, v152
	ds_bpermute_b32 v185, v217, v153
	ds_bpermute_b32 v186, v217, v154
	ds_bpermute_b32 v187, v217, v155
	s_add_u32 s20, s22, 0x90000
	s_addc_u32 s21, s23, 0
	v_cvt_pk_bf16_f32 v156, v46, v47
	v_cvt_pk_bf16_f32 v157, v48, v49
	v_cvt_pk_bf16_f32 v158, v42, v43
	v_cvt_pk_bf16_f32 v159, v44, v45
	ds_bpermute_b32 v188, v217, v156
	ds_bpermute_b32 v189, v217, v157
	ds_bpermute_b32 v190, v217, v158
	ds_bpermute_b32 v191, v217, v159
	v_cvt_pk_bf16_f32 v160, v38, v39
	v_cvt_pk_bf16_f32 v161, v40, v41
	v_cvt_pk_bf16_f32 v162, v34, v35
	v_cvt_pk_bf16_f32 v163, v36, v37
	ds_bpermute_b32 v192, v217, v160
	ds_bpermute_b32 v193, v217, v161
	ds_bpermute_b32 v194, v217, v162
	ds_bpermute_b32 v195, v217, v163
	s_waitcnt lgkmcnt(0)
	global_store_dwordx4 v216, v[180:183], s[10:11] sc0 sc1
	global_store_dwordx4 v216, v[184:187], s[10:11] offset:256 sc0 sc1
	global_store_dwordx4 v216, v[188:191], s[20:21] sc0 sc1
	global_store_dwordx4 v216, v[192:195], s[20:21] offset:256 sc0 sc1
	s_add_u32 s10, s22, 0xa0000
	s_addc_u32 s11, s23, 0
	v_cvt_pk_bf16_f32 v148, v28, v29
	v_cvt_pk_bf16_f32 v149, v30, v31
	v_cvt_pk_bf16_f32 v150, v24, v25
	v_cvt_pk_bf16_f32 v151, v26, v27
	ds_bpermute_b32 v180, v217, v148
	ds_bpermute_b32 v181, v217, v149
	ds_bpermute_b32 v182, v217, v150
	ds_bpermute_b32 v183, v217, v151
	v_cvt_pk_bf16_f32 v152, v20, v21
	v_cvt_pk_bf16_f32 v153, v22, v23
	v_cvt_pk_bf16_f32 v154, v16, v17
	v_cvt_pk_bf16_f32 v155, v18, v19
	ds_bpermute_b32 v184, v217, v152
	ds_bpermute_b32 v185, v217, v153
	ds_bpermute_b32 v186, v217, v154
	ds_bpermute_b32 v187, v217, v155
	s_add_u32 s20, s22, 0xb0000
	s_addc_u32 s21, s23, 0
	v_cvt_pk_bf16_f32 v156, v12, v13
	v_cvt_pk_bf16_f32 v157, v14, v15
	v_cvt_pk_bf16_f32 v158, v8, v9
	v_cvt_pk_bf16_f32 v159, v10, v11
	ds_bpermute_b32 v188, v217, v156
	ds_bpermute_b32 v189, v217, v157
	ds_bpermute_b32 v190, v217, v158
	ds_bpermute_b32 v191, v217, v159
	v_cvt_pk_bf16_f32 v160, v4, v5
	v_cvt_pk_bf16_f32 v161, v6, v7
	v_cvt_pk_bf16_f32 v162, v0, v1
	v_cvt_pk_bf16_f32 v163, v2, v3
	ds_bpermute_b32 v192, v217, v160
	ds_bpermute_b32 v193, v217, v161
	ds_bpermute_b32 v194, v217, v162
	ds_bpermute_b32 v195, v217, v163
	s_waitcnt lgkmcnt(0)
	global_store_dwordx4 v216, v[180:183], s[10:11] sc0 sc1
	global_store_dwordx4 v216, v[184:187], s[10:11] offset:256 sc0 sc1
	global_store_dwordx4 v216, v[188:191], s[20:21] sc0 sc1
	global_store_dwordx4 v216, v[192:195], s[20:21] offset:256 sc0 sc1
	s_branch .LBB0_364
